# attention phase: only one wave per SIMD (waves 0-3) pulls tasks from the queues; phase is bound by the longest task's per-tile latency
# speedup vs baseline: 1.0262x; 1.0023x over previous
; __device__ __forceinline__ void attn_phase(const Ctx& c, ArgsP a, int l, int ctr_slot) {
;     unsigned* ctr0 = (unsigned*)(c.ws + WS_CTL) + 64 * ctr_slot;
;     const int myq = (int)(__builtin_amdgcn_s_getreg((3 << 11) | 20) & 7u);
;     for (int qi = 0; qi < 8; ++qi) {
;         const int q = (myq + qi) & 7;
;         unsigned* ctr = ctr0 + 64 * q;
;         for (;;) {
;             int t = 0;
;             if (c.lane == 0) t = (int)atomicAdd(ctr, 1u);
;             t = __builtin_amdgcn_readfirstlane(t);
;             if (t >= 448) break;
;             Ctx ct = c; { int ln = c.lane; asm volatile("" : "+v"(ln)); ct.lane = ln; }
;             int ll = l; asm volatile("" : "+s"(ll));
.LBB0_119:
	s_and_b64 vcc, exec, s[4:5]
	s_cbranch_vccz .LBB0_332
	s_cmp_gt_i32 s2, 2
	s_mov_b64 s[4:5], -1
	s_cbranch_scc0 .LBB0_328
	s_add_u32 s3, s48, 0x25700000
	v_writelane_b32 v255, s3, 20
	s_addc_u32 s3, s49, 0
	v_writelane_b32 v255, s3, 21
	s_cmp_lt_i32 s2, 4
	s_cbranch_scc1 .LBB0_235
	s_cmp_gt_i32 s2, 4
	s_cbranch_scc0 .LBB0_220
	s_lshl_b32 s2, s67, 9
	s_ashr_i32 s3, s2, 31
	v_readlane_b32 s4, v254, 47
	s_add_u32 s2, s4, s2
	v_readlane_b32 s4, v254, 48
	s_addc_u32 s3, s4, s3
	s_lshl_b64 s[2:3], s[2:3], 2
	v_writelane_b32 v255, s67, 22
	s_add_u32 s2, s48, s2
	v_writelane_b32 v255, s2, 30
	s_addc_u32 s2, s49, s3
	v_writelane_b32 v255, s2, 31
	s_getreg_b32 s2, hwreg(HW_REG_XCC_ID, 0, 4)
	v_writelane_b32 v255, s2, 32
	s_add_u32 s2, s48, 0x2b400000
	v_writelane_b32 v255, s2, 26
	s_addc_u32 s2, s49, 0
	v_writelane_b32 v255, s2, 28
	s_add_u32 s2, s48, 0x2e900000
	v_writelane_b32 v255, s2, 23
	s_addc_u32 s2, s49, 0
	v_writelane_b32 v255, s2, 24
	v_readlane_b32 s2, v254, 62
	s_lshl_b32 s2, s2, 14
	s_add_i32 s52, s2, 0
	s_add_u32 s77, s48, 0x2dd00000
	s_addc_u32 s2, s49, 0
	s_add_u32 s3, s48, 0x2a700000
	s_addc_u32 s63, s49, 0
	s_add_u32 s88, s48, 0x2d500000
	s_addc_u32 s89, s49, 0
	s_add_u32 s51, s48, 0x2b500000
	s_mov_b32 s67, 0
	v_cmp_eq_u32_e64 s[6:7], 0, v198
	v_writelane_b32 v255, s2, 25
	s_addc_u32 s95, s49, 0
	v_readlane_b32 s4, v254, 62
	s_nop 3
	s_cmp_gt_u32 s4, 3
	s_cbranch_scc1 .LBB0_219
	s_branch .LBB0_125
